# combo2 + P1 unit-seam counted wait: vmcnt(24) on the first two waits of P1's peeled first K-iteration (min 16 epilogue stores on every EpiProj path)
# baseline (speedup 1.0000x reference)
.LBB0_125:
	s_ashr_i32 s77, s76, 31
	s_lshl_b64 s[18:19], s[76:77], 21
	s_add_u32 s58, s86, s18
	s_addc_u32 s59, s87, s19
	s_and_b64 s[18:19], s[6:7], exec
	s_cselect_b32 s11, s59, s9
	s_cselect_b32 s13, s58, s8
	s_ashr_i32 s17, s16, 31
	s_lshl_b64 s[18:19], s[16:17], 21
	s_add_u32 s36, s96, s18
	s_addc_u32 s37, s97, s19
	s_and_b64 s[18:19], s[6:7], exec
	s_cselect_b32 s17, s37, s15
	s_cselect_b32 s20, s36, s14
	s_add_u32 s8, s8, 0x100080
	s_addc_u32 s9, s9, 0
	s_add_u32 s21, s14, 0x100
	s_addc_u32 s28, s15, 0
	s_mov_b32 s29, -2
	ds_read_b128 v[130:133], v176
	ds_read_b128 v[134:137], v176 offset:1024
	ds_read_b128 v[170:173], v176 offset:2048
	ds_read_b128 v[180:183], v176 offset:3072
	ds_read_b128 v[184:187], v177
	ds_read_b128 v[188:191], v177 offset:1024
	ds_read_b128 v[192:195], v177 offset:2048
	ds_read_b128 v[198:201], v177 offset:3072
	s_add_u32 s14, s8, 0xfff00080
	s_addc_u32 s15, s9, -1
	s_cmp_eq_u32 s29, 60
	s_cselect_b32 s19, s11, s15
	s_cselect_b32 s18, s13, s14
	s_cselect_b32 s15, s17, s28
	s_cselect_b32 s14, s20, s21
	s_add_i32 m0, s73, 0xc000
	ds_read_b128 v[202:205], v178
	ds_read_b128 v[206:209], v178 offset:1024
	ds_read_b128 v[210:213], v178 offset:2048
	ds_read_b128 v[214:217], v178 offset:3072
	ds_read_b128 v[218:221], v178 offset:4096
	ds_read_b128 v[222:225], v178 offset:5120
	ds_read_b128 v[226:229], v178 offset:6144
	ds_read_b128 v[230:233], v178 offset:7168
	global_load_lds_dwordx4 v160, s[8:9]
	s_add_i32 m0, s73, 0xe000
	s_nop 0
	global_load_lds_dwordx4 v162, s[8:9]
	s_waitcnt vmcnt(24)
	s_waitcnt lgkmcnt(0)
	s_setprio 1
	s_barrier
	v_mfma_f32_16x16x32_bf16 v[126:129], v[130:133], v[202:205], 0
	v_mfma_f32_16x16x32_bf16 v[122:125], v[170:173], v[202:205], 0
	v_mfma_f32_16x16x32_bf16 v[110:113], v[130:133], v[210:213], 0
	v_mfma_f32_16x16x32_bf16 v[106:109], v[170:173], v[210:213], 0
	v_mfma_f32_16x16x32_bf16 v[94:97], v[130:133], v[218:221], 0
	v_mfma_f32_16x16x32_bf16 v[90:93], v[170:173], v[218:221], 0
	v_mfma_f32_16x16x32_bf16 v[78:81], v[130:133], v[226:229], 0
	v_mfma_f32_16x16x32_bf16 v[74:77], v[170:173], v[226:229], 0
	v_mfma_f32_16x16x32_bf16 v[126:129], v[134:137], v[206:209], v[126:129]
	v_mfma_f32_16x16x32_bf16 v[122:125], v[180:183], v[206:209], v[122:125]
	v_mfma_f32_16x16x32_bf16 v[110:113], v[134:137], v[214:217], v[110:113]
	v_mfma_f32_16x16x32_bf16 v[106:109], v[180:183], v[214:217], v[106:109]
	v_mfma_f32_16x16x32_bf16 v[94:97], v[134:137], v[222:225], v[94:97]
	v_mfma_f32_16x16x32_bf16 v[90:93], v[180:183], v[222:225], v[90:93]
	v_mfma_f32_16x16x32_bf16 v[78:81], v[134:137], v[230:233], v[78:81]
	v_mfma_f32_16x16x32_bf16 v[74:77], v[180:183], v[230:233], v[74:77]
	v_mfma_f32_16x16x32_bf16 v[118:121], v[184:187], v[202:205], 0
	v_mfma_f32_16x16x32_bf16 v[114:117], v[192:195], v[202:205], 0
	v_mfma_f32_16x16x32_bf16 v[102:105], v[184:187], v[210:213], 0
	v_mfma_f32_16x16x32_bf16 v[98:101], v[192:195], v[210:213], 0
	v_mfma_f32_16x16x32_bf16 v[86:89], v[184:187], v[218:221], 0
	v_mfma_f32_16x16x32_bf16 v[82:85], v[192:195], v[218:221], 0
	v_mfma_f32_16x16x32_bf16 v[70:73], v[184:187], v[226:229], 0
	v_mfma_f32_16x16x32_bf16 v[66:69], v[192:195], v[226:229], 0
	v_mfma_f32_16x16x32_bf16 v[118:121], v[188:191], v[206:209], v[118:121]
	v_mfma_f32_16x16x32_bf16 v[114:117], v[198:201], v[206:209], v[114:117]
	v_mfma_f32_16x16x32_bf16 v[102:105], v[188:191], v[214:217], v[102:105]
	v_mfma_f32_16x16x32_bf16 v[98:101], v[198:201], v[214:217], v[98:101]
	v_mfma_f32_16x16x32_bf16 v[86:89], v[188:191], v[222:225], v[86:89]
	v_mfma_f32_16x16x32_bf16 v[82:85], v[198:201], v[222:225], v[82:85]
	v_mfma_f32_16x16x32_bf16 v[70:73], v[188:191], v[230:233], v[70:73]
	v_mfma_f32_16x16x32_bf16 v[66:69], v[198:201], v[230:233], v[66:69]
	s_barrier
	s_setprio 0
	s_add_i32 s30, s69, s35
	s_mov_b32 m0, s30
	ds_read_b128 v[202:205], v178 offset:16384
	ds_read_b128 v[206:209], v178 offset:17408
	ds_read_b128 v[210:213], v178 offset:18432
	ds_read_b128 v[214:217], v178 offset:19456
	ds_read_b128 v[218:221], v178 offset:20480
	ds_read_b128 v[222:225], v178 offset:21504
	ds_read_b128 v[226:229], v178 offset:22528
	ds_read_b128 v[230:233], v178 offset:23552
	global_load_lds_dwordx4 v140, s[14:15]
	s_add_i32 m0, s30, 0x2000
	s_add_u32 s30, s14, 0x100000
	s_addc_u32 s31, s15, 0
	s_add_i32 s38, s70, s35
	global_load_lds_dwordx4 v144, s[14:15]
	s_mov_b32 m0, s38
	global_load_lds_dwordx4 v140, s[30:31]
	s_add_i32 m0, s38, 0x2000
	s_nop 0
	global_load_lds_dwordx4 v144, s[30:31]
	s_mov_b32 m0, s73
	s_nop 0
	global_load_lds_dwordx4 v138, s[18:19]
	s_mov_b32 m0, s66
	s_nop 0
	global_load_lds_dwordx4 v142, s[18:19]
	s_waitcnt vmcnt(24)
	s_waitcnt lgkmcnt(0)
	s_setprio 1
	s_barrier
	v_mfma_f32_16x16x32_bf16 v[62:65], v[130:133], v[202:205], 0
	v_mfma_f32_16x16x32_bf16 v[58:61], v[170:173], v[202:205], 0
	v_mfma_f32_16x16x32_bf16 v[46:49], v[130:133], v[210:213], 0
	v_mfma_f32_16x16x32_bf16 v[42:45], v[170:173], v[210:213], 0
	v_mfma_f32_16x16x32_bf16 v[30:33], v[130:133], v[218:221], 0
	v_mfma_f32_16x16x32_bf16 v[26:29], v[170:173], v[218:221], 0
	v_mfma_f32_16x16x32_bf16 v[14:17], v[130:133], v[226:229], 0
	v_mfma_f32_16x16x32_bf16 v[10:13], v[170:173], v[226:229], 0
	v_mfma_f32_16x16x32_bf16 v[62:65], v[134:137], v[206:209], v[62:65]
	v_mfma_f32_16x16x32_bf16 v[58:61], v[180:183], v[206:209], v[58:61]
	v_mfma_f32_16x16x32_bf16 v[46:49], v[134:137], v[214:217], v[46:49]
	v_mfma_f32_16x16x32_bf16 v[42:45], v[180:183], v[214:217], v[42:45]
	v_mfma_f32_16x16x32_bf16 v[30:33], v[134:137], v[222:225], v[30:33]
	v_mfma_f32_16x16x32_bf16 v[26:29], v[180:183], v[222:225], v[26:29]
	v_mfma_f32_16x16x32_bf16 v[14:17], v[134:137], v[230:233], v[14:17]
	v_mfma_f32_16x16x32_bf16 v[10:13], v[180:183], v[230:233], v[10:13]
	v_mfma_f32_16x16x32_bf16 v[54:57], v[184:187], v[202:205], 0
	v_mfma_f32_16x16x32_bf16 v[50:53], v[192:195], v[202:205], 0
	v_mfma_f32_16x16x32_bf16 v[38:41], v[184:187], v[210:213], 0
	v_mfma_f32_16x16x32_bf16 v[34:37], v[192:195], v[210:213], 0
	v_mfma_f32_16x16x32_bf16 v[22:25], v[184:187], v[218:221], 0
	v_mfma_f32_16x16x32_bf16 v[18:21], v[192:195], v[218:221], 0
	v_mfma_f32_16x16x32_bf16 v[6:9], v[184:187], v[226:229], 0
	v_mfma_f32_16x16x32_bf16 v[2:5], v[192:195], v[226:229], 0
	v_mfma_f32_16x16x32_bf16 v[54:57], v[188:191], v[206:209], v[54:57]
	v_mfma_f32_16x16x32_bf16 v[50:53], v[198:201], v[206:209], v[50:53]
	v_mfma_f32_16x16x32_bf16 v[38:41], v[188:191], v[214:217], v[38:41]
	v_mfma_f32_16x16x32_bf16 v[34:37], v[198:201], v[214:217], v[34:37]
	v_mfma_f32_16x16x32_bf16 v[22:25], v[188:191], v[222:225], v[22:25]
	v_mfma_f32_16x16x32_bf16 v[18:21], v[198:201], v[222:225], v[18:21]
	v_mfma_f32_16x16x32_bf16 v[6:9], v[188:191], v[230:233], v[6:9]
	v_mfma_f32_16x16x32_bf16 v[2:5], v[198:201], v[230:233], v[2:5]
	s_barrier
	s_setprio 0
	s_add_i32 s30, 0, 0x18000
	v_add_u32_e32 v146, s30, v155
	s_add_i32 s31, 0, 0x1c000
	ds_read_b128 v[130:133], v146
	ds_read_b128 v[134:137], v146 offset:1024
	ds_read_b128 v[170:173], v146 offset:2048
	ds_read_b128 v[180:183], v146 offset:3072
	v_add_u32_e32 v146, s31, v155
	ds_read_b128 v[184:187], v146
	ds_read_b128 v[188:191], v146 offset:1024
	ds_read_b128 v[192:195], v146 offset:2048
	ds_read_b128 v[198:201], v146 offset:3072
	s_add_u32 s18, s18, 0x100000
	s_addc_u32 s19, s19, 0
	s_mov_b32 m0, s67
	ds_read_b128 v[202:205], v178 offset:32768
	ds_read_b128 v[206:209], v178 offset:33792
	ds_read_b128 v[210:213], v178 offset:34816
	ds_read_b128 v[214:217], v178 offset:35840
	ds_read_b128 v[218:221], v178 offset:36864
	ds_read_b128 v[222:225], v178 offset:37888
	ds_read_b128 v[226:229], v178 offset:38912
	ds_read_b128 v[230:233], v178 offset:39936
	global_load_lds_dwordx4 v138, s[18:19]
	s_mov_b32 m0, s88
	s_nop 0
	global_load_lds_dwordx4 v142, s[18:19]
	s_waitcnt vmcnt(8)
	s_waitcnt lgkmcnt(0)
	s_setprio 1
	s_barrier
	v_mfma_f32_16x16x32_bf16 v[126:129], v[130:133], v[202:205], v[126:129]
	v_mfma_f32_16x16x32_bf16 v[122:125], v[170:173], v[202:205], v[122:125]
	v_mfma_f32_16x16x32_bf16 v[110:113], v[130:133], v[210:213], v[110:113]
	v_mfma_f32_16x16x32_bf16 v[106:109], v[170:173], v[210:213], v[106:109]
	v_mfma_f32_16x16x32_bf16 v[94:97], v[130:133], v[218:221], v[94:97]
	v_mfma_f32_16x16x32_bf16 v[90:93], v[170:173], v[218:221], v[90:93]
	v_mfma_f32_16x16x32_bf16 v[78:81], v[130:133], v[226:229], v[78:81]
	v_mfma_f32_16x16x32_bf16 v[74:77], v[170:173], v[226:229], v[74:77]
	v_mfma_f32_16x16x32_bf16 v[126:129], v[134:137], v[206:209], v[126:129]
	v_mfma_f32_16x16x32_bf16 v[122:125], v[180:183], v[206:209], v[122:125]
	v_mfma_f32_16x16x32_bf16 v[110:113], v[134:137], v[214:217], v[110:113]
	v_mfma_f32_16x16x32_bf16 v[106:109], v[180:183], v[214:217], v[106:109]
	v_mfma_f32_16x16x32_bf16 v[94:97], v[134:137], v[222:225], v[94:97]
	v_mfma_f32_16x16x32_bf16 v[90:93], v[180:183], v[222:225], v[90:93]
	v_mfma_f32_16x16x32_bf16 v[78:81], v[134:137], v[230:233], v[78:81]
	v_mfma_f32_16x16x32_bf16 v[74:77], v[180:183], v[230:233], v[74:77]
	v_mfma_f32_16x16x32_bf16 v[118:121], v[184:187], v[202:205], v[118:121]
	v_mfma_f32_16x16x32_bf16 v[114:117], v[192:195], v[202:205], v[114:117]
	v_mfma_f32_16x16x32_bf16 v[102:105], v[184:187], v[210:213], v[102:105]
	v_mfma_f32_16x16x32_bf16 v[98:101], v[192:195], v[210:213], v[98:101]
	v_mfma_f32_16x16x32_bf16 v[86:89], v[184:187], v[218:221], v[86:89]
	v_mfma_f32_16x16x32_bf16 v[82:85], v[192:195], v[218:221], v[82:85]
	v_mfma_f32_16x16x32_bf16 v[70:73], v[184:187], v[226:229], v[70:73]
	v_mfma_f32_16x16x32_bf16 v[66:69], v[192:195], v[226:229], v[66:69]
	v_mfma_f32_16x16x32_bf16 v[118:121], v[188:191], v[206:209], v[118:121]
	v_mfma_f32_16x16x32_bf16 v[114:117], v[198:201], v[206:209], v[114:117]
	v_mfma_f32_16x16x32_bf16 v[102:105], v[188:191], v[214:217], v[102:105]
	v_mfma_f32_16x16x32_bf16 v[98:101], v[198:201], v[214:217], v[98:101]
	v_mfma_f32_16x16x32_bf16 v[86:89], v[188:191], v[222:225], v[86:89]
	v_mfma_f32_16x16x32_bf16 v[82:85], v[198:201], v[222:225], v[82:85]
	v_mfma_f32_16x16x32_bf16 v[70:73], v[188:191], v[230:233], v[70:73]
	v_mfma_f32_16x16x32_bf16 v[66:69], v[198:201], v[230:233], v[66:69]
	s_barrier
	s_setprio 0
	s_add_u32 s14, s14, 0x80
	s_addc_u32 s15, s15, 0
	s_add_i32 m0, s35, 0x18000
	ds_read_b128 v[202:205], v178 offset:49152
	ds_read_b128 v[206:209], v178 offset:50176
	ds_read_b128 v[210:213], v178 offset:51200
	ds_read_b128 v[214:217], v178 offset:52224
	ds_read_b128 v[218:221], v178 offset:53248
	ds_read_b128 v[222:225], v178 offset:54272
	ds_read_b128 v[226:229], v178 offset:55296
	ds_read_b128 v[230:233], v178 offset:56320
	global_load_lds_dwordx4 v140, s[14:15]
	s_add_i32 m0, s35, 0x1a000
	s_add_u32 s18, s18, 0xfff00080
	global_load_lds_dwordx4 v144, s[14:15]
	s_addc_u32 s19, s19, -1
	s_add_u32 s14, s14, 0x100000
	s_addc_u32 s15, s15, 0
	s_add_i32 m0, s35, 0x1c000
	s_nop 0
	global_load_lds_dwordx4 v140, s[14:15]
	s_add_i32 m0, s35, 0x1e000
	s_nop 0
	global_load_lds_dwordx4 v144, s[14:15]
	s_mov_b32 m0, s89
	s_nop 0
	global_load_lds_dwordx4 v138, s[18:19]
	s_mov_b32 m0, s68
	s_nop 0
	global_load_lds_dwordx4 v142, s[18:19]
	s_waitcnt vmcnt(8)
	s_waitcnt lgkmcnt(0)
	s_setprio 1
	s_barrier
	v_mfma_f32_16x16x32_bf16 v[62:65], v[130:133], v[202:205], v[62:65]
	v_mfma_f32_16x16x32_bf16 v[58:61], v[170:173], v[202:205], v[58:61]
	v_mfma_f32_16x16x32_bf16 v[46:49], v[130:133], v[210:213], v[46:49]
	v_mfma_f32_16x16x32_bf16 v[42:45], v[170:173], v[210:213], v[42:45]
	v_mfma_f32_16x16x32_bf16 v[30:33], v[130:133], v[218:221], v[30:33]
	v_mfma_f32_16x16x32_bf16 v[26:29], v[170:173], v[218:221], v[26:29]
	v_mfma_f32_16x16x32_bf16 v[14:17], v[130:133], v[226:229], v[14:17]
	v_mfma_f32_16x16x32_bf16 v[10:13], v[170:173], v[226:229], v[10:13]
	v_mfma_f32_16x16x32_bf16 v[62:65], v[134:137], v[206:209], v[62:65]
	v_mfma_f32_16x16x32_bf16 v[58:61], v[180:183], v[206:209], v[58:61]
	v_mfma_f32_16x16x32_bf16 v[46:49], v[134:137], v[214:217], v[46:49]
	v_mfma_f32_16x16x32_bf16 v[42:45], v[180:183], v[214:217], v[42:45]
	v_mfma_f32_16x16x32_bf16 v[30:33], v[134:137], v[222:225], v[30:33]
	v_mfma_f32_16x16x32_bf16 v[26:29], v[180:183], v[222:225], v[26:29]
	v_mfma_f32_16x16x32_bf16 v[14:17], v[134:137], v[230:233], v[14:17]
	v_mfma_f32_16x16x32_bf16 v[10:13], v[180:183], v[230:233], v[10:13]
	v_mfma_f32_16x16x32_bf16 v[54:57], v[184:187], v[202:205], v[54:57]
	v_mfma_f32_16x16x32_bf16 v[50:53], v[192:195], v[202:205], v[50:53]
	v_mfma_f32_16x16x32_bf16 v[38:41], v[184:187], v[210:213], v[38:41]
	v_mfma_f32_16x16x32_bf16 v[34:37], v[192:195], v[210:213], v[34:37]
	v_mfma_f32_16x16x32_bf16 v[22:25], v[184:187], v[218:221], v[22:25]
	v_mfma_f32_16x16x32_bf16 v[18:21], v[192:195], v[218:221], v[18:21]
	v_mfma_f32_16x16x32_bf16 v[6:9], v[184:187], v[226:229], v[6:9]
	v_mfma_f32_16x16x32_bf16 v[2:5], v[192:195], v[226:229], v[2:5]
	v_mfma_f32_16x16x32_bf16 v[54:57], v[188:191], v[206:209], v[54:57]
	v_mfma_f32_16x16x32_bf16 v[50:53], v[198:201], v[206:209], v[50:53]
	v_mfma_f32_16x16x32_bf16 v[38:41], v[188:191], v[214:217], v[38:41]
	v_mfma_f32_16x16x32_bf16 v[34:37], v[198:201], v[214:217], v[34:37]
	v_mfma_f32_16x16x32_bf16 v[22:25], v[188:191], v[222:225], v[22:25]
	v_mfma_f32_16x16x32_bf16 v[18:21], v[198:201], v[222:225], v[18:21]
	v_mfma_f32_16x16x32_bf16 v[6:9], v[188:191], v[230:233], v[6:9]
	v_mfma_f32_16x16x32_bf16 v[2:5], v[198:201], v[230:233], v[2:5]
	s_barrier
	s_setprio 0
	s_add_i32 s29, s29, 2
	s_add_u32 s8, s8, 0x100
	s_addc_u32 s9, s9, 0
	s_add_u32 s21, s21, 0x100
	s_addc_u32 s28, s28, 0
	s_cmp_gt_u32 s29, 61
	.p2align	8
